# up-proj copy workers prefetch the next queue pop (counter load + head atomic) at the start of the current item
# speedup vs baseline: 1.0013x; 1.0013x over previous
.LBB0_1272:
	s_load_dword s3, s[0:1], 0xa8
	s_mov_b64 s[4:5], -1
	s_waitcnt lgkmcnt(0)
	s_add_i32 s3, s3, -16
	s_cmp_lt_i32 s2, s3
	s_cbranch_scc1 .LBB0_1294
	s_load_dwordx4 s[12:15], s[0:1], 0x90
	s_cmp_eq_u32 s3, 0
	s_cselect_b64 s[10:11], -1, 0
	s_cmp_lg_u32 s3, 0
	s_cselect_b64 s[8:9], -1, 0
	s_waitcnt lgkmcnt(0)
	s_add_u32 s16, s14, 0x6330c8c
	s_addc_u32 s17, s15, 0
	s_add_u32 s14, s14, 0x6330c80
	s_waitcnt vmcnt(0)
	v_or_b32_e32 v0, 0x400, v156
	s_addc_u32 s15, s15, 0
	v_or_b32_e32 v2, 0x800, v156
	v_or_b32_e32 v4, 0xc00, v156
	v_or_b32_e32 v6, 0x1000, v156
	v_or_b32_e32 v8, 0x1400, v156
	v_or_b32_e32 v10, 0x1800, v156
	v_or_b32_e32 v12, 0x1c00, v156
	v_or_b32_e32 v14, 0x2000, v156
	v_or_b32_e32 v16, 0x2400, v156
	v_or_b32_e32 v18, 0x2800, v156
	v_or_b32_e32 v20, 0x2c00, v156
	v_or_b32_e32 v22, 0x3000, v156
	v_or_b32_e32 v24, 0x3400, v156
	v_or_b32_e32 v26, 0x3800, v156
	v_or_b32_e32 v28, 0x3c00, v156
	v_or_b32_e32 v30, 0x4000, v156
	v_or_b32_e32 v32, 0x4400, v156
	v_or_b32_e32 v34, 0x4800, v156
	v_or_b32_e32 v36, 0x4c00, v156
	v_or_b32_e32 v38, 0x5000, v156
	v_or_b32_e32 v40, 0x5400, v156
	v_or_b32_e32 v42, 0x5800, v156
	v_or_b32_e32 v146, 0x7c00, v156
	s_movk_i32 s4, 0x7fc0
	s_movk_i32 s6, 0x1c0
	s_add_i32 s26, 0, 0x252f0
	v_lshlrev_b32_e32 v131, 4, v0
	v_cndmask_b32_e64 v0, 0, 1, s[8:9]
	v_mov_b32_e32 v129, 0
	s_movk_i32 s22, 0x2000
	v_or_b32_e32 v130, 0x5c00, v156
	s_movk_i32 s23, 0x6000
	v_or_b32_e32 v132, 0x6000, v156
	v_or_b32_e32 v134, 0x6400, v156
	v_or_b32_e32 v136, 0x6800, v156
	v_or_b32_e32 v138, 0x6c00, v156
	v_or_b32_e32 v140, 0x7000, v156
	v_or_b32_e32 v142, 0x7400, v156
	v_or_b32_e32 v144, 0x7800, v156
	v_cmp_gt_u32_e64 s[4:5], s4, v146
	v_cmp_gt_u32_e64 s[6:7], s6, v156
	s_movk_i32 s27, 0x3ff
	s_mov_b32 s28, 0xb300000
	v_lshlrev_b32_e32 v128, 4, v156
	v_lshlrev_b32_e32 v133, 4, v2
	s_mov_b32 s29, 0xa000
	v_lshlrev_b32_e32 v135, 4, v4
	s_mov_b32 s30, 0xe000
	v_lshlrev_b32_e32 v137, 4, v6
	s_mov_b32 s31, 0x12000
	v_lshlrev_b32_e32 v139, 4, v8
	s_mov_b32 s33, 0x16000
	v_lshlrev_b32_e32 v141, 4, v10
	s_mov_b32 s34, 0x1a000
	v_lshlrev_b32_e32 v143, 4, v12
	s_mov_b32 s35, 0x1e000
	v_lshlrev_b32_e32 v145, 4, v14
	s_mov_b32 s38, 0x22000
	v_lshlrev_b32_e32 v147, 4, v16
	s_mov_b32 s39, 0x26000
	v_lshlrev_b32_e32 v152, 4, v18
	s_mov_b32 s44, 0x2a000
	v_lshlrev_b32_e32 v153, 4, v20
	s_mov_b32 s45, 0x2e000
	v_lshlrev_b32_e32 v154, 4, v22
	s_mov_b32 s46, 0x32000
	v_lshlrev_b32_e32 v155, 4, v24
	s_mov_b32 s47, 0x36000
	v_lshlrev_b32_e32 v157, 4, v26
	s_mov_b32 s48, 0x3a000
	v_lshlrev_b32_e32 v158, 4, v28
	s_mov_b32 s49, 0x3e000
	s_mov_b32 s50, 0x42000
	s_mov_b32 s51, 0x46000
	s_mov_b32 s52, 0x4a000
	s_mov_b32 s53, 0x4e000
	s_mov_b32 s54, 0x52000
	s_mov_b32 s55, 0x56000
	s_mov_b32 s56, 0x5a000
	s_mov_b32 s57, 0x5e000
	s_mov_b32 s58, 0x62000
	s_mov_b32 s59, 0x66000
	s_mov_b32 s60, 0x6a000
	s_mov_b32 s61, 0x6e000
	s_mov_b32 s62, 0x72000
	v_cmp_ne_u32_e64 s[8:9], 1, v0
	v_mov_b32_e32 v159, s26
	v_lshlrev_b32_e32 v160, 4, v30
	v_lshlrev_b32_e32 v161, 4, v32
	v_lshlrev_b32_e32 v162, 4, v34
	v_lshlrev_b32_e32 v163, 4, v36
	v_lshlrev_b32_e32 v164, 4, v38
	v_lshlrev_b32_e32 v165, 4, v40
	v_lshlrev_b32_e32 v166, 4, v42
	s_mov_b32 s3, 0
	s_branch .LBB0_1276

.LBB0_1276:
	s_and_saveexec_b64 s[18:19], s[36:37]
	s_cbranch_execz .LBB0_1284
	s_bitcmp1_b32 s3, 0
	s_cbranch_scc0 .Lpf6_nopf
	s_waitcnt vmcnt(0)
	v_mov_b32_e32 v0, v177
	v_cmp_lt_i32_e32 vcc, 0, v176
	s_cbranch_vccz .LBB0_1283
	s_or_b32 s3, s3, 2
	s_branch .LBB0_1283
.Lpf6_nopf:
	s_bitcmp1_b32 s3, 1
	v_mov_b32_e32 v0, 0x400
	s_cbranch_scc1 .LBB0_1283
	s_and_b64 vcc, exec, s[8:9]
	s_mov_b64 s[20:21], s[10:11]
	s_cbranch_vccnz .LBB0_1279
	global_load_dword v0, v129, s[16:17] sc1
	s_waitcnt vmcnt(0)
	v_cmp_gt_i32_e64 s[20:21], 1, v0

.LBB0_1284:
	s_or_b64 exec, exec, s[18:19]
	s_waitcnt lgkmcnt(0)
	s_barrier
	ds_read_b32 v0, v159
	s_mov_b64 s[18:19], -1
	s_waitcnt lgkmcnt(0)
	s_barrier
	v_cmp_lt_i32_e32 vcc, s27, v0
	v_readfirstlane_b32 s24, v0
	s_cbranch_vccnz .LBB0_1275
	s_and_saveexec_b64 s[20:21], s[36:37]
	s_cbranch_execz .Lpf6_skip
	s_bitcmp1_b32 s3, 1
	s_cbranch_scc1 .Lpf6_no
	global_load_dword v176, v129, s[16:17] sc1
	v_mov_b32_e32 v177, 1
	global_atomic_add v177, v129, v177, s[14:15] sc0
	s_or_b32 s3, s3, 1
	s_branch .Lpf6_skip
.Lpf6_no:
	s_andn2_b32 s3, s3, 1
.Lpf6_skip:
	s_mov_b64 exec, s[20:21]
	s_ashr_i32 s18, s24, 9
	s_ashr_i32 s19, s18, 31
	s_and_b32 s20, s24, 15
	s_lshl_b64 s[18:19], s[18:19], 3
	s_add_u32 s18, s0, s18
	s_addc_u32 s19, s1, s19
	s_load_dwordx2 s[18:19], s[18:19], 0x18
	s_mul_i32 s25, s20, 0x7fc00
	s_lshl_b32 s20, s24, 19
	s_and_b32 s63, s20, 0xf800000
	v_lshlrev_b32_e32 v168, 4, v130
	s_waitcnt lgkmcnt(0)
	s_add_u32 s18, s18, s63
	s_addc_u32 s19, s19, 0
	s_add_u32 s18, s18, s25
	s_addc_u32 s19, s19, 0
	s_add_u32 s20, s18, 0x4000
	s_addc_u32 s21, s19, 0
	v_lshl_add_u64 v[150:151], s[20:21], 0, v[128:129]
	global_load_dwordx4 v[8:11], v128, s[20:21] nt
	v_add_co_u32_e32 v0, vcc, s22, v150
	s_cmpk_lt_u32 s24, 0x200
	s_nop 0
	v_addc_co_u32_e32 v1, vcc, 0, v151, vcc
	global_load_dwordx4 v[12:15], v[0:1], off nt
	global_load_dwordx4 v[16:19], v131, s[20:21] nt
	v_add_co_u32_e32 v0, vcc, s23, v150
	s_cselect_b32 s18, s28, 0x1d300000
	s_nop 0
	v_addc_co_u32_e32 v1, vcc, 0, v151, vcc
	global_load_dwordx4 v[20:23], v[0:1], off nt
	global_load_dwordx4 v[24:27], v133, s[20:21] nt
	v_add_co_u32_e32 v0, vcc, s29, v150
	s_add_u32 s18, s12, s18
	s_nop 0
	v_addc_co_u32_e32 v1, vcc, 0, v151, vcc
	global_load_dwordx4 v[28:31], v[0:1], off nt
	global_load_dwordx4 v[32:35], v135, s[20:21] nt
	v_add_co_u32_e32 v0, vcc, s30, v150
	s_addc_u32 s19, s13, 0
	s_nop 0
	v_addc_co_u32_e32 v1, vcc, 0, v151, vcc
	global_load_dwordx4 v[36:39], v[0:1], off nt
	global_load_dwordx4 v[40:43], v137, s[20:21] nt
	v_add_co_u32_e32 v0, vcc, s31, v150
	s_add_u32 s18, s18, s63
	s_nop 0
	v_addc_co_u32_e32 v1, vcc, 0, v151, vcc
	global_load_dwordx4 v[44:47], v[0:1], off nt
	global_load_dwordx4 v[48:51], v139, s[20:21] nt
	v_add_co_u32_e32 v0, vcc, s33, v150
	s_addc_u32 s19, s19, 0
	s_nop 0
	v_addc_co_u32_e32 v1, vcc, 0, v151, vcc
	global_load_dwordx4 v[52:55], v[0:1], off nt
	global_load_dwordx4 v[56:59], v141, s[20:21] nt
	v_add_co_u32_e32 v0, vcc, s34, v150
	s_add_u32 s18, s18, s25
	s_nop 0
	v_addc_co_u32_e32 v1, vcc, 0, v151, vcc
	global_load_dwordx4 v[60:63], v[0:1], off nt
	global_load_dwordx4 v[64:67], v143, s[20:21] nt
	v_add_co_u32_e32 v0, vcc, s35, v150
	s_addc_u32 s19, s19, 0
	s_nop 0
	v_addc_co_u32_e32 v1, vcc, 0, v151, vcc
	global_load_dwordx4 v[68:71], v[0:1], off nt
	global_load_dwordx4 v[72:75], v145, s[20:21] nt
	v_add_co_u32_e32 v0, vcc, s38, v150
	v_lshl_add_u64 v[148:149], s[18:19], 0, v[128:129]
	s_nop 0
	v_addc_co_u32_e32 v1, vcc, 0, v151, vcc
	global_load_dwordx4 v[76:79], v[0:1], off nt
	global_load_dwordx4 v[80:83], v147, s[20:21] nt
	v_add_co_u32_e32 v0, vcc, s39, v150
	v_lshlrev_b32_e32 v169, 4, v132
	s_nop 0
	v_addc_co_u32_e32 v1, vcc, 0, v151, vcc
	global_load_dwordx4 v[84:87], v[0:1], off nt
	global_load_dwordx4 v[88:91], v152, s[20:21] nt
	v_add_co_u32_e32 v0, vcc, s44, v150
	v_lshlrev_b32_e32 v170, 4, v134
	s_nop 0
	v_addc_co_u32_e32 v1, vcc, 0, v151, vcc
	global_load_dwordx4 v[92:95], v[0:1], off nt
	global_load_dwordx4 v[96:99], v153, s[20:21] nt
	v_add_co_u32_e32 v0, vcc, s45, v150
	v_lshlrev_b32_e32 v171, 4, v136
	s_nop 0
	v_addc_co_u32_e32 v1, vcc, 0, v151, vcc
	global_load_dwordx4 v[100:103], v[0:1], off nt
	global_load_dwordx4 v[104:107], v154, s[20:21] nt
	v_add_co_u32_e32 v0, vcc, s46, v150
	v_lshlrev_b32_e32 v172, 4, v138
	s_nop 0
	v_addc_co_u32_e32 v1, vcc, 0, v151, vcc
	global_load_dwordx4 v[108:111], v[0:1], off nt
	global_load_dwordx4 v[112:115], v155, s[20:21] nt
	v_add_co_u32_e32 v0, vcc, s47, v150
	v_lshlrev_b32_e32 v173, 4, v140
	s_nop 0
	v_addc_co_u32_e32 v1, vcc, 0, v151, vcc
	global_load_dwordx4 v[116:119], v[0:1], off nt
	global_load_dwordx4 v[120:123], v157, s[20:21] nt
	v_add_co_u32_e32 v0, vcc, s48, v150
	v_lshlrev_b32_e32 v174, 4, v142
	s_nop 0
	v_addc_co_u32_e32 v1, vcc, 0, v151, vcc
	global_load_dwordx4 v[124:127], v[0:1], off nt
	global_load_dwordx4 v[4:7], v158, s[20:21] nt
	v_add_co_u32_e32 v0, vcc, s49, v150
	v_lshlrev_b32_e32 v175, 4, v144
	s_nop 0
	v_addc_co_u32_e32 v1, vcc, 0, v151, vcc
	global_load_dwordx4 v[0:3], v[0:1], off nt
	v_lshlrev_b32_e32 v167, 4, v146
	s_waitcnt vmcnt(31)
	global_store_dwordx4 v128, v[8:11], s[18:19] nt
	s_nop 1
	v_add_co_u32_e32 v8, vcc, s22, v148
	s_nop 1
	v_addc_co_u32_e32 v9, vcc, 0, v149, vcc
	s_waitcnt vmcnt(31)
	global_store_dwordx4 v[8:9], v[12:15], off nt
	s_waitcnt vmcnt(31)
	global_store_dwordx4 v131, v[16:19], s[18:19] nt
	v_add_co_u32_e32 v8, vcc, s23, v148
	s_nop 1
	v_addc_co_u32_e32 v9, vcc, 0, v149, vcc
	s_waitcnt vmcnt(31)
	global_store_dwordx4 v[8:9], v[20:23], off nt
	s_waitcnt vmcnt(31)
	global_store_dwordx4 v133, v[24:27], s[18:19] nt
	v_add_co_u32_e32 v8, vcc, s29, v148
	s_nop 1
	v_addc_co_u32_e32 v9, vcc, 0, v149, vcc
	s_waitcnt vmcnt(31)
	global_store_dwordx4 v[8:9], v[28:31], off nt
	s_waitcnt vmcnt(31)
	global_store_dwordx4 v135, v[32:35], s[18:19] nt
	v_add_co_u32_e32 v8, vcc, s30, v148
	s_nop 1
	v_addc_co_u32_e32 v9, vcc, 0, v149, vcc
	s_waitcnt vmcnt(31)
	global_store_dwordx4 v[8:9], v[36:39], off nt
	s_waitcnt vmcnt(31)
	global_store_dwordx4 v137, v[40:43], s[18:19] nt
	v_add_co_u32_e32 v8, vcc, s31, v148
	s_nop 1
	v_addc_co_u32_e32 v9, vcc, 0, v149, vcc
	s_waitcnt vmcnt(31)
	global_store_dwordx4 v[8:9], v[44:47], off nt
	s_waitcnt vmcnt(31)
	global_store_dwordx4 v139, v[48:51], s[18:19] nt
	v_add_co_u32_e32 v8, vcc, s33, v148
	s_nop 1
	v_addc_co_u32_e32 v9, vcc, 0, v149, vcc
	s_waitcnt vmcnt(31)
	global_store_dwordx4 v[8:9], v[52:55], off nt
	s_waitcnt vmcnt(31)
	global_store_dwordx4 v141, v[56:59], s[18:19] nt
	v_add_co_u32_e32 v8, vcc, s34, v148
	s_nop 1
	v_addc_co_u32_e32 v9, vcc, 0, v149, vcc
	s_waitcnt vmcnt(31)
	global_store_dwordx4 v[8:9], v[60:63], off nt
	s_waitcnt vmcnt(31)
	global_store_dwordx4 v143, v[64:67], s[18:19] nt
	v_add_co_u32_e32 v8, vcc, s35, v148
	s_nop 1
	v_addc_co_u32_e32 v9, vcc, 0, v149, vcc
	s_waitcnt vmcnt(31)
	global_store_dwordx4 v[8:9], v[68:71], off nt
	s_waitcnt vmcnt(31)
	global_store_dwordx4 v145, v[72:75], s[18:19] nt
	v_add_co_u32_e32 v8, vcc, s38, v148
	s_nop 1
	v_addc_co_u32_e32 v9, vcc, 0, v149, vcc
	s_waitcnt vmcnt(31)
	global_store_dwordx4 v[8:9], v[76:79], off nt
	s_waitcnt vmcnt(31)
	global_store_dwordx4 v147, v[80:83], s[18:19] nt
	v_add_co_u32_e32 v8, vcc, s39, v148
	s_nop 1
	v_addc_co_u32_e32 v9, vcc, 0, v149, vcc
	s_waitcnt vmcnt(31)
	global_store_dwordx4 v[8:9], v[84:87], off nt
	s_waitcnt vmcnt(31)
	global_store_dwordx4 v152, v[88:91], s[18:19] nt
	v_add_co_u32_e32 v8, vcc, s44, v148
	s_nop 1
	v_addc_co_u32_e32 v9, vcc, 0, v149, vcc
	s_waitcnt vmcnt(31)
	global_store_dwordx4 v[8:9], v[92:95], off nt
	s_waitcnt vmcnt(31)
	global_store_dwordx4 v153, v[96:99], s[18:19] nt
	v_add_co_u32_e32 v8, vcc, s45, v148
	s_nop 1
	v_addc_co_u32_e32 v9, vcc, 0, v149, vcc
	s_waitcnt vmcnt(31)
	global_store_dwordx4 v[8:9], v[100:103], off nt
	s_waitcnt vmcnt(31)
	global_store_dwordx4 v154, v[104:107], s[18:19] nt
	v_add_co_u32_e32 v8, vcc, s46, v148
	s_nop 1
	v_addc_co_u32_e32 v9, vcc, 0, v149, vcc
	s_waitcnt vmcnt(31)
	global_store_dwordx4 v[8:9], v[108:111], off nt
	s_waitcnt vmcnt(31)
	global_store_dwordx4 v155, v[112:115], s[18:19] nt
	v_add_co_u32_e32 v8, vcc, s47, v148
	s_nop 1
	v_addc_co_u32_e32 v9, vcc, 0, v149, vcc
	s_waitcnt vmcnt(31)
	global_store_dwordx4 v[8:9], v[116:119], off nt
	s_waitcnt vmcnt(31)
	global_store_dwordx4 v157, v[120:123], s[18:19] nt
	v_add_co_u32_e32 v8, vcc, s48, v148
	s_nop 1
	v_addc_co_u32_e32 v9, vcc, 0, v149, vcc
	s_waitcnt vmcnt(31)
	global_store_dwordx4 v[8:9], v[124:127], off nt
	s_waitcnt vmcnt(31)
	global_store_dwordx4 v158, v[4:7], s[18:19] nt
	v_add_co_u32_e32 v8, vcc, s49, v148
	s_nop 1
	v_addc_co_u32_e32 v9, vcc, 0, v149, vcc
	s_waitcnt vmcnt(31)
	global_store_dwordx4 v[8:9], v[0:3], off nt
	v_add_co_u32_e32 v8, vcc, s50, v150
	s_nop 1
	v_addc_co_u32_e32 v9, vcc, 0, v151, vcc
	global_load_dwordx4 v[124:127], v160, s[20:21] nt
	global_load_dwordx4 v[92:95], v[8:9], off nt
	v_add_co_u32_e32 v8, vcc, s51, v150
	s_nop 1
	v_addc_co_u32_e32 v9, vcc, 0, v151, vcc
	global_load_dwordx4 v[120:123], v161, s[20:21] nt
	global_load_dwordx4 v[80:83], v[8:9], off nt
	v_add_co_u32_e32 v8, vcc, s52, v150
	s_nop 1
	v_addc_co_u32_e32 v9, vcc, 0, v151, vcc
	global_load_dwordx4 v[112:115], v162, s[20:21] nt
	global_load_dwordx4 v[52:55], v[8:9], off nt
	v_add_co_u32_e32 v8, vcc, s53, v150
	s_nop 1
	v_addc_co_u32_e32 v9, vcc, 0, v151, vcc
	global_load_dwordx4 v[104:107], v163, s[20:21] nt
	global_load_dwordx4 v[44:47], v[8:9], off nt
	v_add_co_u32_e32 v8, vcc, s54, v150
	s_nop 1
	v_addc_co_u32_e32 v9, vcc, 0, v151, vcc
	global_load_dwordx4 v[96:99], v164, s[20:21] nt
	global_load_dwordx4 v[36:39], v[8:9], off nt
	v_add_co_u32_e32 v8, vcc, s55, v150
	s_nop 1
	v_addc_co_u32_e32 v9, vcc, 0, v151, vcc
	global_load_dwordx4 v[84:87], v165, s[20:21] nt
	global_load_dwordx4 v[28:31], v[8:9], off nt
	v_add_co_u32_e32 v8, vcc, s56, v150
	s_nop 1
	v_addc_co_u32_e32 v9, vcc, 0, v151, vcc
	v_add_co_u32_e32 v12, vcc, s57, v150
	global_load_dwordx4 v[56:59], v166, s[20:21] nt
	s_nop 0
	global_load_dwordx4 v[8:11], v[8:9], off nt
	v_addc_co_u32_e32 v13, vcc, 0, v151, vcc
	v_add_co_u32_e32 v16, vcc, s58, v150
	global_load_dwordx4 v[60:63], v168, s[20:21] nt
	s_nop 0
	global_load_dwordx4 v[12:15], v[12:13], off nt
	v_addc_co_u32_e32 v17, vcc, 0, v151, vcc
	v_add_co_u32_e32 v20, vcc, s59, v150
	global_load_dwordx4 v[64:67], v169, s[20:21] nt
	s_nop 0
	global_load_dwordx4 v[16:19], v[16:17], off nt
	v_addc_co_u32_e32 v21, vcc, 0, v151, vcc
	v_add_co_u32_e32 v24, vcc, s60, v150
	global_load_dwordx4 v[68:71], v170, s[20:21] nt
	s_nop 0
	global_load_dwordx4 v[20:23], v[20:21], off nt
	v_addc_co_u32_e32 v25, vcc, 0, v151, vcc
	v_add_co_u32_e32 v32, vcc, s61, v150
	global_load_dwordx4 v[72:75], v171, s[20:21] nt
	s_nop 0
	global_load_dwordx4 v[24:27], v[24:25], off nt
	v_addc_co_u32_e32 v33, vcc, 0, v151, vcc
	v_add_co_u32_e32 v40, vcc, s62, v150
	global_load_dwordx4 v[88:91], v172, s[20:21] nt
	s_nop 0
	global_load_dwordx4 v[32:35], v[32:33], off nt
	v_addc_co_u32_e32 v41, vcc, 0, v151, vcc
	v_add_co_u32_e32 v48, vcc, 0x76000, v150
	global_load_dwordx4 v[100:103], v173, s[20:21] nt
	s_nop 0
	global_load_dwordx4 v[40:43], v[40:41], off nt
	v_addc_co_u32_e32 v49, vcc, 0, v151, vcc
	v_add_co_u32_e32 v76, vcc, 0x7a000, v150
	global_load_dwordx4 v[108:111], v174, s[20:21] nt
	s_nop 0
	global_load_dwordx4 v[48:51], v[48:49], off nt
	v_addc_co_u32_e32 v77, vcc, 0, v151, vcc
	global_load_dwordx4 v[116:119], v175, s[20:21] nt
	s_nop 0
	global_load_dwordx4 v[76:79], v[76:77], off nt
	s_and_saveexec_b64 s[24:25], s[4:5]
	s_cbranch_execz .LBB0_1287
	global_load_dwordx4 v[4:7], v167, s[20:21] nt
